# in-proj GEMM epilogue: rope cos/sin rows for the next 16-row block are loaded before the current block's stores (counted vmcnt(2), no store drain per block)
# speedup vs baseline: 1.0064x; 1.0003x over previous
.LBB0_261:
	s_cmp_lt_u32 s19, 4
	v_pk_mul_f32 v[122:123], v[140:141], s[94:95] op_sel_hi:[1,0]
	v_pk_mul_f32 v[124:125], v[138:139], s[94:95] op_sel_hi:[1,0]
	s_cselect_b64 s[42:43], -1, 0
	v_pk_mul_f32 v[126:127], v[144:145], s[94:95] op_sel_hi:[1,0]
	v_cndmask_b32_e64 v0, v140, v122, s[42:43]
	v_cndmask_b32_e64 v123, v141, v123, s[42:43]
	v_cndmask_b32_e64 v122, v138, v124, s[42:43]
	v_pk_mul_f32 v[128:129], v[142:143], s[94:95] op_sel_hi:[1,0]
	v_cndmask_b32_e64 v124, v139, v125, s[42:43]
	v_cndmask_b32_e64 v125, v144, v126, s[42:43]
	v_cvt_pk_bf16_f32 v122, v122, v124
	v_cvt_pk_bf16_f32 v123, v0, v123
	v_cndmask_b32_e64 v0, 0, 1, s[8:9]
	v_cndmask_b32_e64 v126, v145, v127, s[42:43]
	v_cndmask_b32_e64 v127, v142, v128, s[42:43]
	v_cndmask_b32_e64 v128, v143, v129, s[42:43]
	v_cvt_pk_bf16_f32 v124, v127, v128
	v_cvt_pk_bf16_f32 v125, v125, v126
	v_cmp_ne_u32_e64 s[44:45], 1, v0
	s_and_b64 vcc, exec, s[40:41]
	s_cbranch_vccnz .Lpf_1
	v_or_b32_e32 v190, 16, v168
	v_mov_b32_e32 v191, s12
	v_cndmask_b32_e64 v190, v190, v191, s[36:37]
	v_lshlrev_b32_e32 v190, 6, v190
	v_and_b32_e32 v190, 0xfc0, v190
	v_mov_b32_e32 v191, 0
	v_lshl_add_u64 v[192:193], v[160:161], 0, v[190:191]
	v_lshl_add_u64 v[194:195], v[158:159], 0, v[190:191]
	global_load_dwordx4 v[218:221], v[192:193], off
	global_load_dwordx4 v[222:225], v[192:193], off offset:16
	global_load_dwordx4 v[226:229], v[194:195], off
	global_load_dwordx4 v[230:233], v[194:195], off offset:16
.Lpf_1:
	s_andn2_b64 vcc, exec, s[8:9]
	s_mov_b64 s[8:9], -1
	global_store_dwordx4 v[172:173], v[122:125], off
	s_cbranch_vccnz .LBB0_265
	v_mov_b64_e32 v[128:129], v[116:117]
	v_mov_b64_e32 v[124:125], v[120:121]
	s_and_b64 vcc, exec, s[40:41]
	v_mov_b64_e32 v[126:127], v[114:115]
	v_mov_b64_e32 v[122:123], v[118:119]
	s_cbranch_vccnz .LBB0_264
	v_and_b32_e32 v122, 64, v211
	v_xor_b32_e32 v0, 32, v211
	v_add_u32_e32 v122, 64, v122
	v_cmp_lt_i32_e32 vcc, v0, v122
	s_nop 1
	v_cndmask_b32_e32 v0, v211, v0, vcc
	v_lshlrev_b32_e32 v0, 2, v0
	ds_bpermute_b32 v122, v0, v118
	ds_bpermute_b32 v126, v0, v114
	ds_bpermute_b32 v123, v0, v119
	ds_bpermute_b32 v124, v0, v120
	ds_bpermute_b32 v125, v0, v121
	ds_bpermute_b32 v127, v0, v115
	ds_bpermute_b32 v128, v0, v116
	ds_bpermute_b32 v129, v0, v117
	s_waitcnt lgkmcnt(0)
	v_pk_mul_f32 v[122:123], v[178:179], v[122:123]
	v_pk_mul_f32 v[124:125], v[180:181], v[124:125]
	v_pk_mul_f32 v[126:127], v[176:177], v[126:127]
	v_pk_fma_f32 v[124:125], v[120:121], v[136:137], v[124:125]
	v_pk_mul_f32 v[128:129], v[174:175], v[128:129]
	v_pk_fma_f32 v[122:123], v[118:119], v[134:135], v[122:123]
	v_pk_fma_f32 v[128:129], v[116:117], v[132:133], v[128:129]
	v_pk_fma_f32 v[126:127], v[114:115], v[130:131], v[126:127]

.LBB0_270:
	s_waitcnt vmcnt(2)
	v_mov_b32_e32 v122, v218
	v_mov_b32_e32 v123, v219
	v_mov_b32_e32 v124, v220
	v_mov_b32_e32 v125, v221
	v_mov_b32_e32 v126, v222
	v_mov_b32_e32 v127, v223
	v_mov_b32_e32 v128, v224
	v_mov_b32_e32 v129, v225
	v_mov_b32_e32 v118, v226
	v_mov_b32_e32 v119, v227
	v_mov_b32_e32 v120, v228
	v_mov_b32_e32 v121, v229
	v_mov_b32_e32 v114, v230
	v_mov_b32_e32 v115, v231
	v_mov_b32_e32 v116, v232
	v_mov_b32_e32 v117, v233
	v_pk_mul_f32 v[132:133], v[156:157], v[128:129]
	v_pk_mul_f32 v[138:139], v[156:157], v[124:125]
	v_pk_mul_f32 v[136:137], v[154:155], v[122:123]
	v_pk_mul_f32 v[134:135], v[154:155], v[126:127]
	s_and_b64 vcc, exec, s[44:45]
	s_mov_b64 s[8:9], -1
	s_cbranch_vccnz .LBB0_277
	s_branch .LBB0_274

.LBB0_279:
	v_pk_mul_f32 v[106:107], v[124:125], s[94:95] op_sel_hi:[1,0]
	v_pk_mul_f32 v[108:109], v[122:123], s[94:95] op_sel_hi:[1,0]
	v_pk_mul_f32 v[110:111], v[128:129], s[94:95] op_sel_hi:[1,0]
	v_pk_mul_f32 v[112:113], v[126:127], s[94:95] op_sel_hi:[1,0]
	v_cndmask_b32_e64 v0, v124, v106, s[42:43]
	v_cndmask_b32_e64 v107, v125, v107, s[42:43]
	v_cndmask_b32_e64 v106, v122, v108, s[42:43]
	v_cndmask_b32_e64 v108, v123, v109, s[42:43]
	v_cndmask_b32_e64 v109, v128, v110, s[42:43]
	v_cndmask_b32_e64 v110, v129, v111, s[42:43]
	v_cndmask_b32_e64 v111, v126, v112, s[42:43]
	v_cndmask_b32_e64 v112, v127, v113, s[42:43]
	v_cvt_pk_bf16_f32 v106, v106, v108
	v_cvt_pk_bf16_f32 v107, v0, v107
	v_cvt_pk_bf16_f32 v108, v111, v112
	v_cvt_pk_bf16_f32 v109, v109, v110
	s_and_b64 vcc, exec, s[40:41]
	s_cbranch_vccnz .Lpf_2
	v_or_b32_e32 v190, 32, v168
	v_mov_b32_e32 v191, s12
	v_cndmask_b32_e64 v190, v190, v191, s[36:37]
	v_lshlrev_b32_e32 v190, 6, v190
	v_and_b32_e32 v190, 0xfc0, v190
	v_mov_b32_e32 v191, 0
	v_lshl_add_u64 v[192:193], v[160:161], 0, v[190:191]
	v_lshl_add_u64 v[194:195], v[158:159], 0, v[190:191]
	global_load_dwordx4 v[218:221], v[192:193], off
	global_load_dwordx4 v[222:225], v[192:193], off offset:16
	global_load_dwordx4 v[226:229], v[194:195], off
	global_load_dwordx4 v[230:233], v[194:195], off offset:16
.Lpf_2:
	s_and_b64 vcc, exec, s[44:45]
	s_mov_b64 s[8:9], -1
	global_store_dwordx4 v[130:131], v[106:109], off
	s_cbranch_vccnz .LBB0_283
	v_mov_b64_e32 v[112:113], v[100:101]
	v_mov_b64_e32 v[108:109], v[104:105]
	s_and_b64 vcc, exec, s[40:41]
	v_mov_b64_e32 v[110:111], v[98:99]
	v_mov_b64_e32 v[106:107], v[102:103]
	s_cbranch_vccnz .LBB0_282
	v_and_b32_e32 v106, 64, v211
	v_xor_b32_e32 v0, 32, v211
	v_add_u32_e32 v106, 64, v106
	v_cmp_lt_i32_e32 vcc, v0, v106
	s_nop 1
	v_cndmask_b32_e32 v0, v211, v0, vcc
	v_lshlrev_b32_e32 v0, 2, v0
	ds_bpermute_b32 v106, v0, v102
	ds_bpermute_b32 v110, v0, v98
	ds_bpermute_b32 v107, v0, v103
	ds_bpermute_b32 v108, v0, v104
	ds_bpermute_b32 v109, v0, v105
	ds_bpermute_b32 v111, v0, v99
	ds_bpermute_b32 v112, v0, v100
	ds_bpermute_b32 v113, v0, v101
	s_waitcnt lgkmcnt(0)
	v_pk_mul_f32 v[106:107], v[136:137], v[106:107]
	v_pk_mul_f32 v[108:109], v[138:139], v[108:109]
	v_pk_mul_f32 v[110:111], v[134:135], v[110:111]
	v_pk_fma_f32 v[108:109], v[104:105], v[120:121], v[108:109]
	v_pk_mul_f32 v[112:113], v[132:133], v[112:113]
	v_pk_fma_f32 v[106:107], v[102:103], v[118:119], v[106:107]
	v_pk_fma_f32 v[112:113], v[100:101], v[116:117], v[112:113]
	v_pk_fma_f32 v[110:111], v[98:99], v[114:115], v[110:111]

.LBB0_288:
	s_waitcnt vmcnt(2)
	v_mov_b32_e32 v106, v218
	v_mov_b32_e32 v107, v219
	v_mov_b32_e32 v108, v220
	v_mov_b32_e32 v109, v221
	v_mov_b32_e32 v110, v222
	v_mov_b32_e32 v111, v223
	v_mov_b32_e32 v112, v224
	v_mov_b32_e32 v113, v225
	v_mov_b32_e32 v102, v226
	v_mov_b32_e32 v103, v227
	v_mov_b32_e32 v104, v228
	v_mov_b32_e32 v105, v229
	v_mov_b32_e32 v98, v230
	v_mov_b32_e32 v99, v231
	v_mov_b32_e32 v100, v232
	v_mov_b32_e32 v101, v233
	v_pk_mul_f32 v[116:117], v[156:157], v[112:113]
	v_pk_mul_f32 v[122:123], v[156:157], v[108:109]
	v_pk_mul_f32 v[120:121], v[154:155], v[106:107]
	v_pk_mul_f32 v[118:119], v[154:155], v[110:111]
	s_and_b64 vcc, exec, s[44:45]
	s_mov_b64 s[8:9], -1
	s_cbranch_vccnz .LBB0_295
	s_branch .LBB0_292

.LBB0_297:
	v_pk_mul_f32 v[90:91], v[108:109], s[94:95] op_sel_hi:[1,0]
	v_pk_mul_f32 v[92:93], v[106:107], s[94:95] op_sel_hi:[1,0]
	v_pk_mul_f32 v[94:95], v[112:113], s[94:95] op_sel_hi:[1,0]
	v_pk_mul_f32 v[96:97], v[110:111], s[94:95] op_sel_hi:[1,0]
	v_cndmask_b32_e64 v0, v108, v90, s[42:43]
	v_cndmask_b32_e64 v91, v109, v91, s[42:43]
	v_cndmask_b32_e64 v90, v106, v92, s[42:43]
	v_cndmask_b32_e64 v92, v107, v93, s[42:43]
	v_cndmask_b32_e64 v93, v112, v94, s[42:43]
	v_cndmask_b32_e64 v94, v113, v95, s[42:43]
	v_cndmask_b32_e64 v95, v110, v96, s[42:43]
	v_cndmask_b32_e64 v96, v111, v97, s[42:43]
	v_cvt_pk_bf16_f32 v90, v90, v92
	v_cvt_pk_bf16_f32 v91, v0, v91
	v_cvt_pk_bf16_f32 v92, v95, v96
	v_cvt_pk_bf16_f32 v93, v93, v94
	s_and_b64 vcc, exec, s[40:41]
	s_cbranch_vccnz .Lpf_3
	v_or_b32_e32 v190, 48, v168
	v_mov_b32_e32 v191, s12
	v_cndmask_b32_e64 v190, v190, v191, s[36:37]
	v_lshlrev_b32_e32 v190, 6, v190
	v_and_b32_e32 v190, 0xfc0, v190
	v_mov_b32_e32 v191, 0
	v_lshl_add_u64 v[192:193], v[160:161], 0, v[190:191]
	v_lshl_add_u64 v[194:195], v[158:159], 0, v[190:191]
	global_load_dwordx4 v[218:221], v[192:193], off
	global_load_dwordx4 v[222:225], v[192:193], off offset:16
	global_load_dwordx4 v[226:229], v[194:195], off
	global_load_dwordx4 v[230:233], v[194:195], off offset:16
.Lpf_3:
	s_and_b64 vcc, exec, s[44:45]
	s_mov_b64 s[8:9], -1
	global_store_dwordx4 v[114:115], v[90:93], off
	s_cbranch_vccnz .LBB0_301
	v_mov_b64_e32 v[96:97], v[84:85]
	v_mov_b64_e32 v[92:93], v[88:89]
	s_and_b64 vcc, exec, s[40:41]
	v_mov_b64_e32 v[94:95], v[82:83]
	v_mov_b64_e32 v[90:91], v[86:87]
	s_cbranch_vccnz .LBB0_300
	v_and_b32_e32 v90, 64, v211
	v_xor_b32_e32 v0, 32, v211
	v_add_u32_e32 v90, 64, v90
	v_cmp_lt_i32_e32 vcc, v0, v90
	s_nop 1
	v_cndmask_b32_e32 v0, v211, v0, vcc
	v_lshlrev_b32_e32 v0, 2, v0
	ds_bpermute_b32 v90, v0, v86
	ds_bpermute_b32 v94, v0, v82
	ds_bpermute_b32 v91, v0, v87
	ds_bpermute_b32 v92, v0, v88
	ds_bpermute_b32 v93, v0, v89
	ds_bpermute_b32 v95, v0, v83
	ds_bpermute_b32 v96, v0, v84
	ds_bpermute_b32 v97, v0, v85
	s_waitcnt lgkmcnt(0)
	v_pk_mul_f32 v[90:91], v[120:121], v[90:91]
	v_pk_mul_f32 v[92:93], v[122:123], v[92:93]
	v_pk_mul_f32 v[94:95], v[118:119], v[94:95]
	v_pk_fma_f32 v[92:93], v[88:89], v[104:105], v[92:93]
	v_pk_mul_f32 v[96:97], v[116:117], v[96:97]
	v_pk_fma_f32 v[90:91], v[86:87], v[102:103], v[90:91]
	v_pk_fma_f32 v[96:97], v[84:85], v[100:101], v[96:97]
	v_pk_fma_f32 v[94:95], v[82:83], v[98:99], v[94:95]

.LBB0_306:
	s_waitcnt vmcnt(2)
	v_mov_b32_e32 v90, v218
	v_mov_b32_e32 v91, v219
	v_mov_b32_e32 v92, v220
	v_mov_b32_e32 v93, v221
	v_mov_b32_e32 v94, v222
	v_mov_b32_e32 v95, v223
	v_mov_b32_e32 v96, v224
	v_mov_b32_e32 v97, v225
	v_mov_b32_e32 v86, v226
	v_mov_b32_e32 v87, v227
	v_mov_b32_e32 v88, v228
	v_mov_b32_e32 v89, v229
	v_mov_b32_e32 v82, v230
	v_mov_b32_e32 v83, v231
	v_mov_b32_e32 v84, v232
	v_mov_b32_e32 v85, v233
	v_pk_mul_f32 v[100:101], v[156:157], v[96:97]
	v_pk_mul_f32 v[106:107], v[156:157], v[92:93]
	v_pk_mul_f32 v[104:105], v[154:155], v[90:91]
	v_pk_mul_f32 v[102:103], v[154:155], v[94:95]
	s_and_b64 vcc, exec, s[44:45]
	s_mov_b64 s[8:9], -1
	s_cbranch_vccnz .LBB0_313
	s_branch .LBB0_310

.LBB0_315:
	v_pk_mul_f32 v[74:75], v[92:93], s[94:95] op_sel_hi:[1,0]
	v_pk_mul_f32 v[76:77], v[90:91], s[94:95] op_sel_hi:[1,0]
	v_pk_mul_f32 v[78:79], v[96:97], s[94:95] op_sel_hi:[1,0]
	v_pk_mul_f32 v[80:81], v[94:95], s[94:95] op_sel_hi:[1,0]
	v_cndmask_b32_e64 v0, v92, v74, s[42:43]
	v_cndmask_b32_e64 v75, v93, v75, s[42:43]
	v_cndmask_b32_e64 v74, v90, v76, s[42:43]
	v_cndmask_b32_e64 v76, v91, v77, s[42:43]
	v_cndmask_b32_e64 v77, v96, v78, s[42:43]
	v_cndmask_b32_e64 v78, v97, v79, s[42:43]
	v_cndmask_b32_e64 v79, v94, v80, s[42:43]
	v_cndmask_b32_e64 v80, v95, v81, s[42:43]
	v_cvt_pk_bf16_f32 v74, v74, v76
	v_cvt_pk_bf16_f32 v75, v0, v75
	v_cvt_pk_bf16_f32 v76, v79, v80
	v_cvt_pk_bf16_f32 v77, v77, v78
	s_and_b64 vcc, exec, s[40:41]
	s_cbranch_vccnz .Lpf_4
	v_add_u32_e32 v191, 0x80, v168
	v_mov_b32_e32 v190, v182
	v_lshrrev_b32_e32 v191, 6, v191
	v_cndmask_b32_e64 v190, v190, v191, s[36:37]
	v_lshlrev_b32_e32 v190, 6, v190
	v_and_b32_e32 v190, 0xfc0, v190
	v_mov_b32_e32 v191, 0
	v_lshl_add_u64 v[192:193], v[160:161], 0, v[190:191]
	v_lshl_add_u64 v[194:195], v[158:159], 0, v[190:191]
	global_load_dwordx4 v[218:221], v[192:193], off
	global_load_dwordx4 v[222:225], v[192:193], off offset:16
	global_load_dwordx4 v[226:229], v[194:195], off
	global_load_dwordx4 v[230:233], v[194:195], off offset:16
.Lpf_4:
	s_and_b64 vcc, exec, s[44:45]
	s_mov_b64 s[8:9], -1
	global_store_dwordx4 v[98:99], v[74:77], off
	s_cbranch_vccnz .LBB0_319
	v_mov_b64_e32 v[80:81], v[68:69]
	v_mov_b64_e32 v[76:77], v[72:73]
	s_and_b64 vcc, exec, s[40:41]
	v_mov_b64_e32 v[78:79], v[66:67]
	v_mov_b64_e32 v[74:75], v[70:71]
	s_cbranch_vccnz .LBB0_318
	v_and_b32_e32 v74, 64, v211
	v_xor_b32_e32 v0, 32, v211
	v_add_u32_e32 v74, 64, v74
	v_cmp_lt_i32_e32 vcc, v0, v74
	s_nop 1
	v_cndmask_b32_e32 v0, v211, v0, vcc
	v_lshlrev_b32_e32 v0, 2, v0
	ds_bpermute_b32 v74, v0, v70
	ds_bpermute_b32 v78, v0, v66
	ds_bpermute_b32 v75, v0, v71
	ds_bpermute_b32 v76, v0, v72
	ds_bpermute_b32 v77, v0, v73
	ds_bpermute_b32 v79, v0, v67
	ds_bpermute_b32 v80, v0, v68
	ds_bpermute_b32 v81, v0, v69
	s_waitcnt lgkmcnt(0)
	v_pk_mul_f32 v[74:75], v[104:105], v[74:75]
	v_pk_mul_f32 v[76:77], v[106:107], v[76:77]
	v_pk_mul_f32 v[78:79], v[102:103], v[78:79]
	v_pk_fma_f32 v[76:77], v[72:73], v[88:89], v[76:77]
	v_pk_mul_f32 v[80:81], v[100:101], v[80:81]
	v_pk_fma_f32 v[74:75], v[70:71], v[86:87], v[74:75]
	v_pk_fma_f32 v[80:81], v[68:69], v[84:85], v[80:81]
	v_pk_fma_f32 v[78:79], v[66:67], v[82:83], v[78:79]

.LBB0_324:
	s_waitcnt vmcnt(2)
	v_mov_b32_e32 v74, v218
	v_mov_b32_e32 v75, v219
	v_mov_b32_e32 v76, v220
	v_mov_b32_e32 v77, v221
	v_mov_b32_e32 v78, v222
	v_mov_b32_e32 v79, v223
	v_mov_b32_e32 v80, v224
	v_mov_b32_e32 v81, v225
	v_mov_b32_e32 v70, v226
	v_mov_b32_e32 v71, v227
	v_mov_b32_e32 v72, v228
	v_mov_b32_e32 v73, v229
	v_mov_b32_e32 v66, v230
	v_mov_b32_e32 v67, v231
	v_mov_b32_e32 v68, v232
	v_mov_b32_e32 v69, v233
	v_pk_mul_f32 v[84:85], v[156:157], v[80:81]
	v_pk_mul_f32 v[90:91], v[156:157], v[76:77]
	v_pk_mul_f32 v[88:89], v[154:155], v[74:75]
	v_pk_mul_f32 v[86:87], v[154:155], v[78:79]
	s_and_b64 vcc, exec, s[44:45]
	s_mov_b64 s[8:9], -1
	s_cbranch_vccnz .LBB0_331
	s_branch .LBB0_328

.LBB0_333:
	v_pk_mul_f32 v[58:59], v[76:77], s[94:95] op_sel_hi:[1,0]
	v_pk_mul_f32 v[60:61], v[74:75], s[94:95] op_sel_hi:[1,0]
	v_pk_mul_f32 v[62:63], v[80:81], s[94:95] op_sel_hi:[1,0]
	v_pk_mul_f32 v[64:65], v[78:79], s[94:95] op_sel_hi:[1,0]
	v_cndmask_b32_e64 v0, v76, v58, s[42:43]
	v_cndmask_b32_e64 v59, v77, v59, s[42:43]
	v_cndmask_b32_e64 v58, v74, v60, s[42:43]
	v_cndmask_b32_e64 v60, v75, v61, s[42:43]
	v_cndmask_b32_e64 v61, v80, v62, s[42:43]
	v_cndmask_b32_e64 v62, v81, v63, s[42:43]
	v_cndmask_b32_e64 v63, v78, v64, s[42:43]
	v_cndmask_b32_e64 v64, v79, v65, s[42:43]
	v_cvt_pk_bf16_f32 v58, v58, v60
	v_cvt_pk_bf16_f32 v59, v0, v59
	v_cvt_pk_bf16_f32 v60, v63, v64
	v_cvt_pk_bf16_f32 v61, v61, v62
	s_and_b64 vcc, exec, s[40:41]
	s_cbranch_vccnz .Lpf_5
	v_add_u32_e32 v191, 0x80, v168
	v_add_u32_e32 v190, 0x90, v168
	v_lshrrev_b32_e32 v191, 6, v191
	v_cndmask_b32_e64 v190, v190, v191, s[36:37]
	v_lshlrev_b32_e32 v190, 6, v190
	v_and_b32_e32 v190, 0xfc0, v190
	v_mov_b32_e32 v191, 0
	v_lshl_add_u64 v[192:193], v[160:161], 0, v[190:191]
	v_lshl_add_u64 v[194:195], v[158:159], 0, v[190:191]
	global_load_dwordx4 v[218:221], v[192:193], off
	global_load_dwordx4 v[222:225], v[192:193], off offset:16
	global_load_dwordx4 v[226:229], v[194:195], off
	global_load_dwordx4 v[230:233], v[194:195], off offset:16
.Lpf_5:
	s_and_b64 vcc, exec, s[44:45]
	s_mov_b64 s[8:9], -1
	global_store_dwordx4 v[82:83], v[58:61], off
	s_cbranch_vccnz .LBB0_337
	v_mov_b64_e32 v[64:65], v[52:53]
	v_mov_b64_e32 v[60:61], v[56:57]
	s_and_b64 vcc, exec, s[40:41]
	v_mov_b64_e32 v[62:63], v[50:51]
	v_mov_b64_e32 v[58:59], v[54:55]
	s_cbranch_vccnz .LBB0_336
	v_and_b32_e32 v58, 64, v211
	v_xor_b32_e32 v0, 32, v211
	v_add_u32_e32 v58, 64, v58
	v_cmp_lt_i32_e32 vcc, v0, v58
	s_nop 1
	v_cndmask_b32_e32 v0, v211, v0, vcc
	v_lshlrev_b32_e32 v0, 2, v0
	ds_bpermute_b32 v58, v0, v54
	ds_bpermute_b32 v62, v0, v50
	ds_bpermute_b32 v59, v0, v55
	ds_bpermute_b32 v60, v0, v56
	ds_bpermute_b32 v61, v0, v57
	ds_bpermute_b32 v63, v0, v51
	ds_bpermute_b32 v64, v0, v52
	ds_bpermute_b32 v65, v0, v53
	s_waitcnt lgkmcnt(0)
	v_pk_mul_f32 v[58:59], v[88:89], v[58:59]
	v_pk_mul_f32 v[60:61], v[90:91], v[60:61]
	v_pk_mul_f32 v[62:63], v[86:87], v[62:63]
	v_pk_fma_f32 v[60:61], v[56:57], v[72:73], v[60:61]
	v_pk_mul_f32 v[64:65], v[84:85], v[64:65]
	v_pk_fma_f32 v[58:59], v[54:55], v[70:71], v[58:59]
	v_pk_fma_f32 v[64:65], v[52:53], v[68:69], v[64:65]
	v_pk_fma_f32 v[62:63], v[50:51], v[66:67], v[62:63]

.LBB0_342:
	s_waitcnt vmcnt(2)
	v_mov_b32_e32 v58, v218
	v_mov_b32_e32 v59, v219
	v_mov_b32_e32 v60, v220
	v_mov_b32_e32 v61, v221
	v_mov_b32_e32 v62, v222
	v_mov_b32_e32 v63, v223
	v_mov_b32_e32 v64, v224
	v_mov_b32_e32 v65, v225
	v_mov_b32_e32 v54, v226
	v_mov_b32_e32 v55, v227
	v_mov_b32_e32 v56, v228
	v_mov_b32_e32 v57, v229
	v_mov_b32_e32 v50, v230
	v_mov_b32_e32 v51, v231
	v_mov_b32_e32 v52, v232
	v_mov_b32_e32 v53, v233
	v_pk_mul_f32 v[68:69], v[156:157], v[64:65]
	v_pk_mul_f32 v[74:75], v[156:157], v[60:61]
	v_pk_mul_f32 v[72:73], v[154:155], v[58:59]
	v_pk_mul_f32 v[70:71], v[154:155], v[62:63]
	s_and_b64 vcc, exec, s[44:45]
	s_mov_b64 s[8:9], -1
	s_cbranch_vccnz .LBB0_349
	s_branch .LBB0_346

.LBB0_351:
	v_pk_mul_f32 v[42:43], v[60:61], s[94:95] op_sel_hi:[1,0]
	v_pk_mul_f32 v[44:45], v[58:59], s[94:95] op_sel_hi:[1,0]
	v_pk_mul_f32 v[46:47], v[64:65], s[94:95] op_sel_hi:[1,0]
	v_pk_mul_f32 v[48:49], v[62:63], s[94:95] op_sel_hi:[1,0]
	v_cndmask_b32_e64 v0, v60, v42, s[42:43]
	v_cndmask_b32_e64 v43, v61, v43, s[42:43]
	v_cndmask_b32_e64 v42, v58, v44, s[42:43]
	v_cndmask_b32_e64 v44, v59, v45, s[42:43]
	v_cndmask_b32_e64 v45, v64, v46, s[42:43]
	v_cndmask_b32_e64 v46, v65, v47, s[42:43]
	v_cndmask_b32_e64 v47, v62, v48, s[42:43]
	v_cndmask_b32_e64 v48, v63, v49, s[42:43]
	v_cvt_pk_bf16_f32 v42, v42, v44
	v_cvt_pk_bf16_f32 v43, v0, v43
	v_cvt_pk_bf16_f32 v44, v47, v48
	v_cvt_pk_bf16_f32 v45, v45, v46
	s_and_b64 vcc, exec, s[40:41]
	s_cbranch_vccnz .Lpf_6
	v_add_u32_e32 v191, 0x80, v168
	v_add_u32_e32 v190, 0xa0, v168
	v_lshrrev_b32_e32 v191, 6, v191
	v_cndmask_b32_e64 v190, v190, v191, s[36:37]
	v_lshlrev_b32_e32 v190, 6, v190
	v_and_b32_e32 v190, 0xfc0, v190
	v_mov_b32_e32 v191, 0
	v_lshl_add_u64 v[192:193], v[160:161], 0, v[190:191]
	v_lshl_add_u64 v[194:195], v[158:159], 0, v[190:191]
	global_load_dwordx4 v[218:221], v[192:193], off
	global_load_dwordx4 v[222:225], v[192:193], off offset:16
	global_load_dwordx4 v[226:229], v[194:195], off
	global_load_dwordx4 v[230:233], v[194:195], off offset:16
.Lpf_6:
	s_and_b64 vcc, exec, s[44:45]
	s_mov_b64 s[8:9], -1
	global_store_dwordx4 v[66:67], v[42:45], off
	s_cbranch_vccnz .LBB0_355
	v_mov_b64_e32 v[48:49], v[36:37]
	v_mov_b64_e32 v[44:45], v[40:41]
	s_and_b64 vcc, exec, s[40:41]
	v_mov_b64_e32 v[46:47], v[34:35]
	v_mov_b64_e32 v[42:43], v[38:39]
	s_cbranch_vccnz .LBB0_354
	v_and_b32_e32 v42, 64, v211
	v_xor_b32_e32 v0, 32, v211
	v_add_u32_e32 v42, 64, v42
	v_cmp_lt_i32_e32 vcc, v0, v42
	s_nop 1
	v_cndmask_b32_e32 v0, v211, v0, vcc
	v_lshlrev_b32_e32 v0, 2, v0
	ds_bpermute_b32 v42, v0, v38
	ds_bpermute_b32 v46, v0, v34
	ds_bpermute_b32 v43, v0, v39
	ds_bpermute_b32 v44, v0, v40
	ds_bpermute_b32 v45, v0, v41
	ds_bpermute_b32 v47, v0, v35
	ds_bpermute_b32 v48, v0, v36
	ds_bpermute_b32 v49, v0, v37
	s_waitcnt lgkmcnt(0)
	v_pk_mul_f32 v[42:43], v[72:73], v[42:43]
	v_pk_mul_f32 v[44:45], v[74:75], v[44:45]
	v_pk_mul_f32 v[46:47], v[70:71], v[46:47]
	v_pk_fma_f32 v[44:45], v[40:41], v[56:57], v[44:45]
	v_pk_mul_f32 v[48:49], v[68:69], v[48:49]
	v_pk_fma_f32 v[42:43], v[38:39], v[54:55], v[42:43]
	v_pk_fma_f32 v[48:49], v[36:37], v[52:53], v[48:49]
	v_pk_fma_f32 v[46:47], v[34:35], v[50:51], v[46:47]

.LBB0_360:
	s_waitcnt vmcnt(2)
	v_mov_b32_e32 v42, v218
	v_mov_b32_e32 v43, v219
	v_mov_b32_e32 v44, v220
	v_mov_b32_e32 v45, v221
	v_mov_b32_e32 v46, v222
	v_mov_b32_e32 v47, v223
	v_mov_b32_e32 v48, v224
	v_mov_b32_e32 v49, v225
	v_mov_b32_e32 v38, v226
	v_mov_b32_e32 v39, v227
	v_mov_b32_e32 v40, v228
	v_mov_b32_e32 v41, v229
	v_mov_b32_e32 v34, v230
	v_mov_b32_e32 v35, v231
	v_mov_b32_e32 v36, v232
	v_mov_b32_e32 v37, v233
	v_pk_mul_f32 v[52:53], v[156:157], v[48:49]
	v_pk_mul_f32 v[58:59], v[156:157], v[44:45]
	v_pk_mul_f32 v[56:57], v[154:155], v[42:43]
	v_pk_mul_f32 v[54:55], v[154:155], v[46:47]
	s_and_b64 vcc, exec, s[44:45]
	s_mov_b64 s[8:9], -1
	s_cbranch_vccnz .LBB0_367
	s_branch .LBB0_364

.LBB0_369:
	v_pk_mul_f32 v[26:27], v[44:45], s[94:95] op_sel_hi:[1,0]
	v_pk_mul_f32 v[28:29], v[42:43], s[94:95] op_sel_hi:[1,0]
	v_pk_mul_f32 v[30:31], v[48:49], s[94:95] op_sel_hi:[1,0]
	v_pk_mul_f32 v[32:33], v[46:47], s[94:95] op_sel_hi:[1,0]
	v_cndmask_b32_e64 v0, v44, v26, s[42:43]
	v_cndmask_b32_e64 v27, v45, v27, s[42:43]
	v_cndmask_b32_e64 v26, v42, v28, s[42:43]
	v_cndmask_b32_e64 v28, v43, v29, s[42:43]
	v_cndmask_b32_e64 v29, v48, v30, s[42:43]
	v_cndmask_b32_e64 v30, v49, v31, s[42:43]
	v_cndmask_b32_e64 v31, v46, v32, s[42:43]
	v_cndmask_b32_e64 v32, v47, v33, s[42:43]
	v_cvt_pk_bf16_f32 v26, v26, v28
	v_cvt_pk_bf16_f32 v27, v0, v27
	v_cvt_pk_bf16_f32 v28, v31, v32
	v_cvt_pk_bf16_f32 v29, v29, v30
	s_and_b64 vcc, exec, s[40:41]
	s_cbranch_vccnz .Lpf_7
	v_add_u32_e32 v191, 0x80, v168
	v_add_u32_e32 v190, 0xb0, v168
	v_lshrrev_b32_e32 v191, 6, v191
	v_cndmask_b32_e64 v190, v190, v191, s[36:37]
	v_lshlrev_b32_e32 v190, 6, v190
	v_and_b32_e32 v190, 0xfc0, v190
	v_mov_b32_e32 v191, 0
	v_lshl_add_u64 v[192:193], v[160:161], 0, v[190:191]
	v_lshl_add_u64 v[194:195], v[158:159], 0, v[190:191]
	global_load_dwordx4 v[218:221], v[192:193], off
	global_load_dwordx4 v[222:225], v[192:193], off offset:16
	global_load_dwordx4 v[226:229], v[194:195], off
	global_load_dwordx4 v[230:233], v[194:195], off offset:16
.Lpf_7:
	s_and_b64 vcc, exec, s[44:45]
	s_mov_b64 s[8:9], -1
	global_store_dwordx4 v[50:51], v[26:29], off
	s_cbranch_vccnz .LBB0_373
	v_mov_b64_e32 v[32:33], v[20:21]
	v_mov_b64_e32 v[28:29], v[24:25]
	s_and_b64 vcc, exec, s[40:41]
	v_mov_b64_e32 v[30:31], v[18:19]
	v_mov_b64_e32 v[26:27], v[22:23]
	s_cbranch_vccnz .LBB0_372
	v_and_b32_e32 v26, 64, v211
	v_xor_b32_e32 v0, 32, v211
	v_add_u32_e32 v26, 64, v26
	v_cmp_lt_i32_e32 vcc, v0, v26
	s_nop 1
	v_cndmask_b32_e32 v0, v211, v0, vcc
	v_lshlrev_b32_e32 v0, 2, v0
	ds_bpermute_b32 v26, v0, v22
	ds_bpermute_b32 v30, v0, v18
	ds_bpermute_b32 v27, v0, v23
	ds_bpermute_b32 v28, v0, v24
	ds_bpermute_b32 v29, v0, v25
	ds_bpermute_b32 v31, v0, v19
	ds_bpermute_b32 v32, v0, v20
	ds_bpermute_b32 v33, v0, v21
	s_waitcnt lgkmcnt(0)
	v_pk_mul_f32 v[26:27], v[56:57], v[26:27]
	v_pk_mul_f32 v[28:29], v[58:59], v[28:29]
	v_pk_mul_f32 v[30:31], v[54:55], v[30:31]
	v_pk_fma_f32 v[28:29], v[24:25], v[40:41], v[28:29]
	v_pk_mul_f32 v[32:33], v[52:53], v[32:33]
	v_pk_fma_f32 v[26:27], v[22:23], v[38:39], v[26:27]
	v_pk_fma_f32 v[32:33], v[20:21], v[36:37], v[32:33]
	v_pk_fma_f32 v[30:31], v[18:19], v[34:35], v[30:31]

.LBB0_378:
	s_waitcnt vmcnt(2)
	v_mov_b32_e32 v26, v218
	v_mov_b32_e32 v27, v219
	v_mov_b32_e32 v28, v220
	v_mov_b32_e32 v29, v221
	v_mov_b32_e32 v30, v222
	v_mov_b32_e32 v31, v223
	v_mov_b32_e32 v32, v224
	v_mov_b32_e32 v33, v225
	v_mov_b32_e32 v22, v226
	v_mov_b32_e32 v23, v227
	v_mov_b32_e32 v24, v228
	v_mov_b32_e32 v25, v229
	v_mov_b32_e32 v18, v230
	v_mov_b32_e32 v19, v231
	v_mov_b32_e32 v20, v232
	v_mov_b32_e32 v21, v233
	v_pk_mul_f32 v[36:37], v[156:157], v[32:33]
	v_pk_mul_f32 v[42:43], v[156:157], v[28:29]
	v_pk_mul_f32 v[40:41], v[154:155], v[26:27]
	v_pk_mul_f32 v[38:39], v[154:155], v[30:31]
	s_and_b64 vcc, exec, s[44:45]
	s_mov_b64 s[8:9], -1
	s_cbranch_vccnz .LBB0_385
	s_branch .LBB0_382
